# static priority A/B, other half: waves 0-3 (instead of 4-7) at s_setprio 1 in the FoX prompt key-tile loop
# baseline (speedup 1.0000x reference)
; #define GAS __attribute__((address_space(1)))
; #define AT_LOAD(t) do { _Pragma("unroll") for (int i_ = 0; i_ < 2; ++i_) { const int c_ = tid + 512 * i_, row_ = c_ >> 4, ch_ = c_ & 15; \
;         kr[i_] = *(const GAS u32x4*)(Kg + (size_t)(64 * (t) + row_) * NP + ch_ * 8); vr[i_] = *(const GAS u32x4*)(Vg + (size_t)(64 * (t) + row_) * NP + ch_ * 8); } } while (0)
; #define AT_STORE(buf) do { _Pragma("unroll") for (int i_ = 0; i_ < 2; ++i_) { const int c_ = tid + 512 * i_, row_ = c_ >> 4, ch_ = c_ & 15; \
;         *(LAS u32x4*)(L + AT_K + (buf) * 17408 + row_ * 272 + ch_ * 16) = kr[i_]; *(LAS u32x4*)(L + AT_V + (buf) * 20480 + row_ * AVP + ch_ * 16) = vr[i_]; } } while (0)
; __device__ __forceinline__ void fox_prompt_unit(LAS char* L, const bf16_t* P, const float* lfT, bf16_t* MIX, int b, int h, int qb, const int wv) {
;     ...
;     const bf16_t* Kg = P + rowb * NP + PC_KB + h * 128; const bf16_t* Vg = P + rowb * NP + PC_VB + h * 128;
;     u32x4 kr[2], vr[2];
;     ...
;     bf16x8 qf[8];
;     { const bf16_t* Qg = P + (rowb + 256 * qb + 32 * wid + r32) * NP + PC_QB + h * 128 + 8 * hi;
; #pragma unroll
;         for (int kk = 0; kk < 8; ++kk) qf[kk] = *(const GAS bf16x8*)(Qg + 16 * kk); }
;     f32x16 o[4];
; #pragma unroll
;     for (int d = 0; d < 4; ++d)
; #pragma unroll
;         for (int r = 0; r < 16; ++r) o[d][r] = 0.f;
;     float m = -INFINITY, l = 0.f;
;     AT_LOAD(0); AT_STORE(0);
;     __syncthreads();
.LBB0_196:
	s_or_b64 exec, exec, s[0:1]
	s_lshl_b32 s7, s7, 2
	s_lshl_b32 s0, s6, 12
	s_mul_i32 s6, s6, 0x3000000
	s_add_u32 s1, s20, s6
	s_addc_u32 s14, s21, 0
	s_lshl_b32 s8, s15, 8
	s_sub_i32 s0, s0, s8
	s_lshl_b32 s9, s9, 5
	s_lshl_b32 s6, s2, 7
	s_addk_i32 s0, 0xf00
	s_ashr_i32 s16, s9, 31
	s_add_u32 s17, s9, s0
	s_addc_u32 s16, s16, 0
	s_lshl_b32 s2, s2, 8
	s_add_u32 s0, s1, s2
	v_and_b32_e32 v2, 0x78, v10
	s_addc_u32 s1, s14, 0
	v_lshlrev_b32_e32 v2, 1, v2
	v_mov_b32_e32 v3, v1
	v_lshl_add_u64 v[2:3], s[0:1], 0, v[2:3]
	s_mov_b64 s[0:1], 0x2000
	v_lshl_add_u64 v[154:155], v[2:3], 0, s[0:1]
	s_mov_b64 s[0:1], 0x2800
	v_ashrrev_i32_e32 v6, 4, v0
	v_add_u32_e32 v0, 0x200, v0
	v_lshl_add_u64 v[156:157], v[2:3], 0, s[0:1]
	v_mad_i64_i32 v[2:3], s[0:1], v6, s63, v[154:155]
	v_ashrrev_i32_e32 v7, 4, v0
	v_mad_i64_i32 v[4:5], s[0:1], v6, s63, v[156:157]
	global_load_dwordx4 v[98:101], v[2:3], off
	global_load_dwordx4 v[102:105], v[4:5], off
	v_mad_i64_i32 v[2:3], s[0:1], v7, s63, v[154:155]
	v_and_b32_e32 v9, 31, v14
	v_mad_i64_i32 v[4:5], s[0:1], v7, s63, v[156:157]
	global_load_dwordx4 v[106:109], v[2:3], off
	global_load_dwordx4 v[110:113], v[4:5], off
	v_or_b32_e32 v152, s17, v9
	v_mov_b64_e32 v[2:3], s[20:21]
	v_mad_u64_u32 v[2:3], s[0:1], v152, s63, v[2:3]
	v_mov_b32_e32 v0, 0x3000
	v_lshrrev_b32_e32 v8, 5, v8
	v_mad_i32_i24 v3, s16, v0, v3
	v_lshl_add_u64 v[2:3], v[2:3], 0, s[2:3]
	v_lshlrev_b32_e32 v0, 4, v8
	v_lshl_add_u64 v[2:3], v[2:3], 0, v[0:1]
	s_mov_b64 s[0:1], 0x1800
	v_lshl_add_u64 v[4:5], v[2:3], 0, s[0:1]
	v_add_co_u32_e32 v2, vcc, s60, v2
	v_lshlrev_b32_e32 v164, 2, v8
	s_nop 0
	v_addc_co_u32_e32 v3, vcc, 0, v3, vcc
	global_load_dwordx4 v[114:117], v[4:5], off offset:32
	global_load_dwordx4 v[118:121], v[4:5], off offset:64
	global_load_dwordx4 v[122:125], v[4:5], off offset:96
	global_load_dwordx4 v[126:129], v[4:5], off offset:128
	global_load_dwordx4 v[130:133], v[4:5], off offset:160
	global_load_dwordx4 v[134:137], v[4:5], off offset:192
	global_load_dwordx4 v[138:141], v[2:3], off offset:2048
	global_load_dwordx4 v[142:145], v[4:5], off offset:224
	v_lshlrev_b32_e32 v3, 4, v14
	v_and_b32_e32 v2, 16, v14
	v_lshrrev_b32_e32 v4, 2, v14
	v_lshlrev_b32_e32 v5, 2, v14
	v_and_b32_e32 v3, 0xf0, v3
	v_mul_lo_u32 v165, v6, s56
	v_mul_lo_u32 v166, v6, s18
	v_mul_u32_u24_e32 v8, 0x110, v9
	v_and_or_b32 v2, v5, 12, v2
	v_add_u32_e32 v167, 0, v3
	v_mul_lo_u32 v168, v7, s56
	v_mul_lo_u32 v169, v7, s18
	v_and_or_b32 v3, v4, 3, v164
	v_lshlrev_b32_e32 v2, 1, v2
	v_add3_u32 v170, 0, v8, v0
	v_add_u32_e32 v4, v167, v165
	v_add_u32_e32 v5, v167, v166
	v_add_u32_e32 v8, v167, v168
	v_add_u32_e32 v10, v167, v169
	v_mul_u32_u24_e32 v3, 0x140, v3
	s_add_i32 s0, 0, 0x12800
	v_mov_b32_e32 v14, v1
	v_mov_b32_e32 v15, v1
	v_or_b32_e32 v171, s9, v9
	v_add3_u32 v172, 0, v3, v2
	v_add_u32_e32 v173, s0, v0
	v_add_u32_e32 v175, 64, v7
	v_add_u32_e32 v176, 64, v6
	v_mov_b32_e32 v0, v1
	v_mov_b32_e32 v2, v1
	v_mov_b32_e32 v3, v1
	v_mov_b32_e32 v6, v1
	v_mov_b32_e32 v7, v1
	v_mov_b32_e32 v9, v1
	v_mov_b32_e32 v11, v1
	v_mov_b32_e32 v12, v1
	v_mov_b32_e32 v13, v1
	s_waitcnt vmcnt(11)
	ds_write_b128 v4, v[98:101]
	s_waitcnt vmcnt(10)
	ds_write_b128 v5, v[102:105] offset:34816
	s_waitcnt vmcnt(9)
	ds_write_b128 v8, v[106:109]
	s_waitcnt vmcnt(8)
	ds_write_b128 v10, v[110:113] offset:34816
	v_mov_b32_e32 v4, v1
	v_mov_b32_e32 v5, v1
	v_mov_b32_e32 v8, v1
	v_mov_b32_e32 v10, v1
	v_mov_b64_e32 v[64:65], v[14:15]
	v_mov_b64_e32 v[48:49], v[14:15]
	v_mov_b64_e32 v[32:33], v[14:15]
	s_lshl_b32 s0, s15, 2
	v_mov_b64_e32 v[62:63], v[12:13]
	v_mov_b64_e32 v[60:61], v[10:11]
	v_mov_b64_e32 v[58:59], v[8:9]
	v_mov_b64_e32 v[56:57], v[6:7]
	v_mov_b64_e32 v[54:55], v[4:5]
	v_mov_b64_e32 v[52:53], v[2:3]
	v_mov_b64_e32 v[50:51], v[0:1]
	v_mov_b64_e32 v[46:47], v[12:13]
	v_mov_b64_e32 v[44:45], v[10:11]
	v_mov_b64_e32 v[42:43], v[8:9]
	v_mov_b64_e32 v[40:41], v[6:7]
	v_mov_b64_e32 v[38:39], v[4:5]
	v_mov_b64_e32 v[36:37], v[2:3]
	v_mov_b64_e32 v[34:35], v[0:1]
	v_mov_b64_e32 v[30:31], v[12:13]
	v_mov_b64_e32 v[28:29], v[10:11]
	v_mov_b64_e32 v[26:27], v[8:9]
	v_mov_b64_e32 v[24:25], v[6:7]
	v_mov_b64_e32 v[22:23], v[4:5]
	v_mov_b64_e32 v[20:21], v[2:3]
	v_mov_b64_e32 v[18:19], v[0:1]
	v_mov_b64_e32 v[16:17], v[14:15]
	s_mov_b32 s2, 0
	v_mov_b32_e32 v153, s16
	s_or_b32 s14, s9, 31
	v_or_b32_e32 v174, s8, v164
	s_sub_i32 s15, s0, 64
	v_mov_b32_e32 v177, 0
	v_mov_b32_e32 v158, 0xff800000
	v_mov_b64_e32 v[14:15], v[12:13]
	v_mov_b64_e32 v[12:13], v[10:11]
	v_mov_b64_e32 v[10:11], v[8:9]
	v_mov_b64_e32 v[8:9], v[6:7]
	v_mov_b64_e32 v[6:7], v[4:5]
	v_mov_b64_e32 v[4:5], v[2:3]
	v_mov_b64_e32 v[2:3], v[0:1]
	s_mov_b32 s17, 0
	s_waitcnt vmcnt(0) lgkmcnt(0)
	s_barrier
	s_cmpk_gt_i32 s73, 0xff00
	s_cbranch_scc0 .Lfp_noprio
	s_setprio 1
